# v37 + dead-instruction elimination: the two x = 0 + x adds in the attention softmax row-sum chains (group A and group B loops) removed
# baseline (speedup 1.0000x reference)
.LBB0_144:
	s_nop 5
	v_exp_f32_e32 v112, v96
	s_nop 1
	v_exp_f32_e32 v113, v80
	v_exp_f32_e32 v114, v97
	v_exp_f32_e32 v115, v81
	v_exp_f32_e32 v116, v98
	v_exp_f32_e32 v117, v82
	v_add_f32_e32 v80, v113, v112
	v_add_f32_e32 v81, v115, v114
	v_exp_f32_e32 v118, v99
	v_exp_f32_e32 v119, v83
	v_add_f32_e32 v80, v81, v80
	v_add_f32_e32 v81, v117, v116
	v_exp_f32_e32 v120, v100
	v_exp_f32_e32 v121, v84
	v_add_f32_e32 v81, v81, v80
	v_exp_f32_e32 v80, v101
	v_exp_f32_e32 v82, v85
	v_add_f32_e32 v83, v119, v118
	v_add_f32_e32 v81, v83, v81
	v_add_f32_e32 v83, v121, v120
	v_pk_add_f32 v[84:85], v[82:83], v[80:81]
	v_exp_f32_e32 v81, v102
	v_pk_add_f32 v[84:85], v[84:85], v[84:85] op_sel_hi:[0,1]
	v_exp_f32_e32 v83, v86
	v_exp_f32_e32 v84, v103
	v_exp_f32_e32 v96, v87
	v_exp_f32_e32 v98, v89
	v_add_f32_e32 v97, v83, v81
	v_exp_f32_e32 v102, v91
	v_pk_add_f32 v[86:87], v[96:97], v[84:85]
	v_exp_f32_e32 v85, v104
	v_pk_add_f32 v[86:87], v[86:87], v[86:87] op_sel_hi:[0,1]
	v_exp_f32_e32 v97, v88
	v_exp_f32_e32 v86, v105
	v_exp_f32_e32 v104, v93
	s_add_u32 s66, s66, 0x20000
	v_add_f32_e32 v99, v97, v85
	v_pk_add_f32 v[88:89], v[98:99], v[86:87]
	v_exp_f32_e32 v87, v106
	v_pk_add_f32 v[100:101], v[88:89], v[88:89] op_sel_hi:[0,1]
	v_exp_f32_e32 v99, v90
	v_exp_f32_e32 v100, v107
	s_addc_u32 s67, s67, 0
	s_addk_i32 s71, 0x4000
	v_add_f32_e32 v103, v99, v87
	v_pk_add_f32 v[88:89], v[102:103], v[100:101]
	v_exp_f32_e32 v101, v108
	v_pk_add_f32 v[90:91], v[88:89], v[88:89] op_sel_hi:[0,1]
	v_exp_f32_e32 v103, v92
	v_exp_f32_e32 v90, v109
	v_exp_f32_e32 v108, v95
	s_add_i32 s0, s99, 1
	v_add_f32_e32 v105, v103, v101
	v_pk_add_f32 v[88:89], v[104:105], v[90:91]
	v_exp_f32_e32 v91, v110
	v_pk_add_f32 v[106:107], v[88:89], v[88:89] op_sel_hi:[0,1]
	v_exp_f32_e32 v105, v94
	v_exp_f32_e32 v106, v111
	v_cvt_pk_bf16_f32 v92, v112, v114
	v_cvt_pk_bf16_f32 v93, v116, v118
	v_add_f32_e32 v109, v105, v91
	v_pk_add_f32 v[88:89], v[108:109], v[106:107]
	v_cvt_pk_bf16_f32 v94, v120, v80
	v_add_f32_e32 v88, v88, v89
	v_add_f32_e32 v205, v205, v88
	v_cvt_pk_bf16_f32 v95, v81, v84
	v_cvt_pk_bf16_f32 v88, v85, v86
	v_cvt_pk_bf16_f32 v89, v87, v100
	v_cvt_pk_bf16_f32 v90, v101, v90
	v_cvt_pk_bf16_f32 v91, v91, v106
	v_cvt_pk_bf16_f32 v84, v113, v115
	v_cvt_pk_bf16_f32 v85, v117, v119
	v_cvt_pk_bf16_f32 v86, v121, v82
	v_cvt_pk_bf16_f32 v87, v83, v96
	v_cvt_pk_bf16_f32 v80, v97, v98
	v_cvt_pk_bf16_f32 v81, v99, v102
	v_cvt_pk_bf16_f32 v82, v103, v104
	v_cvt_pk_bf16_f32 v83, v105, v108
	s_cmp_eq_u32 s99, s88
	v_subrev_u32_e32 v209, 64, v209
	s_cbranch_scc1 .LBB0_148
	s_mov_b32 s99, s0
	s_cmp_ge_u32 s99, s88
	s_mov_b64 s[0:1], -1
	s_cbranch_scc1 .LBB0_105

.LBB0_191:
	s_add_i32 s101, s70, 3
	s_add_u32 vcc_lo, s66, 0xfc000000
	s_addc_u32 vcc_hi, s67, -1
	s_add_i32 s100, s93, 0xffff4000
	s_and_b32 s100, s100, 0xc000
	s_add_i32 s100, s100, 0x10000
	v_add_u32_e32 v212, s100, v190
	v_add_u32_e32 v213, s100, v205
	v_add_u32_e32 v214, s100, v187
	v_add_u32_e32 v215, s100, v202
	v_add_u32_e32 v229, s100, v188
	v_add_u32_e32 v246, s100, v201
	v_add_u32_e32 v247, s100, v189
	v_add_u32_e32 v248, s100, v200
	ds_read_b64_tr_b16 v[230:231], v212
	ds_read_b64_tr_b16 v[232:233], v213 offset:2048
	ds_read_b64_tr_b16 v[234:235], v214
	ds_read_b64_tr_b16 v[236:237], v215 offset:2048
	ds_read_b64_tr_b16 v[238:239], v229
	ds_read_b64_tr_b16 v[240:241], v246 offset:2048
	v_exp_f32_e32 v114, v96
	v_exp_f32_e32 v115, v80
	v_exp_f32_e32 v116, v97
	v_exp_f32_e32 v117, v81
	v_exp_f32_e32 v118, v98
	v_exp_f32_e32 v119, v82
	v_exp_f32_e32 v120, v99
	v_exp_f32_e32 v121, v83
	v_add_f32_e32 v80, v115, v114
	v_add_f32_e32 v81, v117, v116
	v_add_f32_e32 v80, v81, v80
	v_add_f32_e32 v81, v119, v118
	v_add_f32_e32 v80, v81, v80
	v_add_f32_e32 v81, v121, v120
	v_exp_f32_e32 v122, v100
	v_exp_f32_e32 v123, v84
	v_add_f32_e32 v81, v81, v80
	v_exp_f32_e32 v80, v101
	v_exp_f32_e32 v82, v85
	v_add_f32_e32 v83, v123, v122
	v_exp_f32_e32 v98, v87
	v_exp_f32_e32 v100, v89
	v_pk_add_f32 v[84:85], v[82:83], v[80:81]
	v_exp_f32_e32 v81, v102
	v_pk_add_f32 v[84:85], v[84:85], v[84:85] op_sel_hi:[0,1]
	v_exp_f32_e32 v83, v86
	v_exp_f32_e32 v84, v103
	v_exp_f32_e32 v102, v91
	v_exp_f32_e32 v112, v95
	v_add_f32_e32 v99, v83, v81
	v_pk_add_f32 v[86:87], v[98:99], v[84:85]
	v_exp_f32_e32 v85, v104
	v_pk_add_f32 v[86:87], v[86:87], v[86:87] op_sel_hi:[0,1]
	v_exp_f32_e32 v99, v88
	v_exp_f32_e32 v86, v105
	v_add_f32_e32 v101, v99, v85
	v_pk_add_f32 v[88:89], v[100:101], v[86:87]
	v_exp_f32_e32 v87, v106
	v_pk_add_f32 v[96:97], v[88:89], v[88:89] op_sel_hi:[0,1]
	v_exp_f32_e32 v101, v90
	v_exp_f32_e32 v96, v107
	v_exp_f32_e32 v106, v93
	v_add_f32_e32 v103, v101, v87
	v_pk_add_f32 v[88:89], v[102:103], v[96:97]
	v_exp_f32_e32 v97, v108
	v_pk_add_f32 v[104:105], v[88:89], v[88:89] op_sel_hi:[0,1]
	v_exp_f32_e32 v103, v92
	v_exp_f32_e32 v104, v109
	v_cvt_pk_bf16_f32 v93, v81, v84
	v_add_f32_e32 v107, v103, v97
	v_pk_add_f32 v[88:89], v[106:107], v[104:105]
	v_exp_f32_e32 v105, v110
	v_pk_add_f32 v[108:109], v[88:89], v[88:89] op_sel_hi:[0,1]
	v_exp_f32_e32 v107, v94
	v_exp_f32_e32 v108, v111
	v_cvt_pk_bf16_f32 v81, v101, v102
	v_add_f32_e32 v113, v107, v105
	v_pk_add_f32 v[88:89], v[112:113], v[108:109]
	v_cvt_pk_bf16_f32 v90, v114, v116
	v_add_f32_e32 v88, v88, v89
	v_cvt_pk_bf16_f32 v91, v118, v120
	v_cvt_pk_bf16_f32 v92, v122, v80
	v_cvt_pk_bf16_f32 v95, v87, v96
	v_cvt_pk_bf16_f32 v87, v83, v98
	v_cvt_pk_bf16_f32 v80, v99, v100
	v_cvt_pk_bf16_f32 v94, v85, v86
	v_cvt_pk_bf16_f32 v96, v97, v104
	v_cvt_pk_bf16_f32 v86, v123, v82
	v_cvt_pk_bf16_f32 v82, v103, v106
	ds_read_b64_tr_b16 v[242:243], v247
	ds_read_b64_tr_b16 v[244:245], v248 offset:2048
	s_waitcnt lgkmcnt(6)
	v_mfma_f32_32x32x16_bf16 v[2:17], v[90:93], v[230:233], v[2:17]
	v_cvt_pk_bf16_f32 v97, v105, v108
	v_cvt_pk_bf16_f32 v83, v107, v112
	ds_read_b64_tr_b16 v[230:231], v212 offset:4096
	ds_read_b64_tr_b16 v[232:233], v213 offset:6144
	s_waitcnt lgkmcnt(6)
	v_mfma_f32_32x32x16_bf16 v[18:33], v[90:93], v[234:237], v[18:33]
	s_cmp_ge_u32 s101, s92
	s_cbranch_scc1 .Lattn_a_nodma0
	s_and_b32 s100, s93, 0xc000
	s_add_i32 s100, s100, s63
	s_mov_b32 m0, s100
	s_nop 0
	global_load_lds_dwordx4 v192, vcc
